# first grid barrier: sixteen XCC census loads and sixteen placement-test loads issued together (were one round trip each)
# baseline (speedup 1.0000x reference)
; __device__ __forceinline__ unsigned xb_ld(unsigned* p)              { return __hip_atomic_load(p, __ATOMIC_RELAXED, __HIP_MEMORY_SCOPE_AGENT); }
; __device__ __forceinline__ void xcd_barrier_complete(unsigned* bar, unsigned x, unsigned& nloc, unsigned& nx) {
;     ...
;     for (;;) {
;         sum = 0u; cnt = 0u; mine = 0u;
; #pragma unroll
;         for (unsigned j = 0; j < 16; ++j) { const unsigned c = xb_ld(&bar[XB_XCNT(j)]); sum += c; cnt += (c > 0u) ? 1u : 0u; mine = (j == x) ? c : mine; }
;         if (sum == G) break;
;         __builtin_amdgcn_s_sleep(1);
;         if ((++sp & 255u) == 0u) { if (xb_ld(&bar[XB_TMO])) break; if (sp > XB_SPIN_CAP) { atomicAdd(&bar[XB_TMO], 1u); break; } }
;     }
.LBB0_363:
	v_readlane_b32 s6, v252, 34
	v_readlane_b32 s7, v252, 35
	v_readlane_b32 s1, v252, 31
	s_mov_b64 s[8:9], -1
	s_waitcnt lgkmcnt(0)
	s_nop 1
	global_load_dword v1, v99, s[6:7] sc1
	v_readlane_b32 s6, v252, 36
	v_readlane_b32 s7, v252, 37
	s_nop 4
	global_load_dword v2, v99, s[6:7] sc1
	v_readlane_b32 s6, v252, 38
	v_readlane_b32 s7, v252, 39
	s_nop 0
	s_nop 0
	s_nop 2
	global_load_dword v3, v99, s[6:7] sc1
	v_readlane_b32 s6, v252, 40
	v_readlane_b32 s7, v252, 41
	s_nop 0
	s_nop 0
	s_nop 2
	global_load_dword v4, v99, s[6:7] sc1
	v_readlane_b32 s6, v252, 42
	v_readlane_b32 s7, v252, 43
	s_nop 0
	s_nop 0
	s_nop 2
	global_load_dword v5, v99, s[6:7] sc1
	v_readlane_b32 s6, v252, 44
	v_readlane_b32 s7, v252, 45
	s_nop 0
	s_nop 0
	s_nop 2
	global_load_dword v6, v99, s[6:7] sc1
	v_readlane_b32 s6, v252, 46
	v_readlane_b32 s7, v252, 47
	s_nop 0
	s_nop 0
	s_nop 2
	global_load_dword v7, v99, s[6:7] sc1
	v_readlane_b32 s6, v252, 48
	v_readlane_b32 s7, v252, 49
	s_nop 0
	s_nop 0
	s_nop 2
	global_load_dword v8, v99, s[6:7] sc1
	v_readlane_b32 s6, v252, 50
	v_readlane_b32 s7, v252, 51
	s_nop 0
	s_nop 0
	s_nop 2
	global_load_dword v9, v99, s[6:7] sc1
	v_readlane_b32 s6, v252, 52
	v_readlane_b32 s7, v252, 53
	s_nop 0
	s_nop 0
	s_nop 2
	global_load_dword v10, v99, s[6:7] sc1
	v_readlane_b32 s6, v252, 54
	v_readlane_b32 s7, v252, 55
	s_nop 0
	s_nop 0
	s_nop 2
	global_load_dword v11, v99, s[6:7] sc1
	v_readlane_b32 s6, v252, 56
	v_readlane_b32 s7, v252, 57
	s_nop 0
	s_nop 0
	s_nop 2
	global_load_dword v12, v99, s[6:7] sc1
	v_readlane_b32 s6, v252, 58
	v_readlane_b32 s7, v252, 59
	s_nop 0
	s_nop 0
	s_nop 2
	global_load_dword v13, v99, s[6:7] sc1
	v_readlane_b32 s6, v252, 60
	v_readlane_b32 s7, v252, 61
	s_nop 0
	s_nop 0
	s_nop 2
	global_load_dword v14, v99, s[6:7] sc1
	v_readlane_b32 s6, v252, 62
	v_readlane_b32 s7, v252, 63
	s_nop 0
	s_nop 0
	s_nop 2
	global_load_dword v15, v99, s[6:7] sc1
	v_readlane_b32 s6, v253, 0
	v_readlane_b32 s7, v253, 1
	s_nop 0
	s_nop 0
	s_nop 2
	global_load_dword v16, v99, s[6:7] sc1
	s_mov_b64 s[6:7], -1
	s_waitcnt vmcnt(0)
	v_add_u32_e32 v17, v2, v1
	v_add_u32_e32 v17, v17, v3
	v_add_u32_e32 v17, v17, v4
	v_add_u32_e32 v17, v17, v5
	v_add_u32_e32 v17, v17, v6
	v_add_u32_e32 v17, v17, v7
	v_add_u32_e32 v17, v17, v8
	v_add_u32_e32 v17, v17, v9
	v_add_u32_e32 v17, v17, v10
	v_add_u32_e32 v17, v17, v11
	v_add_u32_e32 v17, v17, v12
	v_add_u32_e32 v17, v17, v13
	v_add_u32_e32 v17, v17, v14
	v_add_u32_e32 v17, v17, v15
	v_add_u32_e32 v17, v17, v16
	v_cmp_eq_u32_e32 vcc, s1, v17
	s_cbranch_vccnz .LBB0_362
	s_and_b32 s6, s4, 0xff
	s_cmp_eq_u32 s6, 0
	s_mov_b64 s[6:7], -1
	s_mov_b64 s[10:11], -1
	s_sleep 1
	s_cbranch_scc1 .LBB0_367
	s_and_b64 vcc, exec, s[10:11]
	s_cbranch_vccz .LBB0_362

; __device__ __forceinline__ unsigned xb_ld(unsigned* p)              { return __hip_atomic_load(p, __ATOMIC_RELAXED, __HIP_MEMORY_SCOPE_AGENT); }
; __global__ void __launch_bounds__(512, 2) hybrid_fwd(Args args) {
;     ...
;             if (threadIdx.x == 0) {
;                 unsigned* bw = (unsigned*)(args.ws + WS_CTL) + CW_BAR;
;                 const unsigned per = (unsigned)G / 8u; bool ok = (G % 8 == 0);
; #pragma unroll
;                 for (unsigned j = 0; j < 16; ++j) { const unsigned c = xb_ld(&bw[XB_XCNT(j)]); ok = ok && (c == (j < 8 ? per : 0u)); }
;                 const unsigned rank = cw[10];
;                 cw[12] = ok ? bar.x * per + rank : (unsigned)vcu;
;                 cw[13] = ok ? rank * 8u + bar.x : (unsigned)bx;
.LBB0_478:
	s_or_b64 exec, exec, s[2:3]
	s_waitcnt lgkmcnt(0)
	s_barrier
	s_mov_b64 s[34:35], exec
	v_readlane_b32 s2, v252, 10
	v_readlane_b32 s3, v252, 11
	s_and_b64 s[2:3], s[34:35], s[2:3]
	s_mov_b64 exec, s[2:3]
	s_cbranch_execz .LBB0_484
	v_readlane_b32 s2, v252, 34
	v_readlane_b32 s3, v252, 35
	v_readlane_b32 s1, v255, 23
	v_readlane_b32 s16, v252, 4
	v_readlane_b32 s17, v252, 5
	v_mov_b32_e32 v1, s1
	v_readlane_b32 s1, v253, 50
	global_load_dword v2, v99, s[2:3] sc1
	v_readlane_b32 s2, v252, 36
	v_readlane_b32 s3, v252, 37
	s_nop 0
	s_nop 0
	s_nop 2
	global_load_dword v3, v99, s[2:3] sc1
	v_readlane_b32 s2, v252, 38
	v_readlane_b32 s3, v252, 39
	s_nop 0
	s_nop 3
	global_load_dword v4, v99, s[2:3] sc1
	v_readlane_b32 s2, v252, 40
	v_readlane_b32 s3, v252, 41
	s_nop 0
	s_nop 0
	s_nop 2
	global_load_dword v5, v99, s[2:3] sc1
	v_readlane_b32 s2, v252, 42
	v_readlane_b32 s3, v252, 43
	s_nop 0
	s_nop 0
	s_nop 2
	global_load_dword v6, v99, s[2:3] sc1
	v_readlane_b32 s2, v252, 44
	v_readlane_b32 s3, v252, 45
	s_nop 0
	s_nop 0
	s_nop 2
	global_load_dword v7, v99, s[2:3] sc1
	v_readlane_b32 s2, v252, 46
	v_readlane_b32 s3, v252, 47
	s_nop 0
	s_nop 0
	s_nop 2
	global_load_dword v8, v99, s[2:3] sc1
	v_readlane_b32 s2, v252, 48
	v_readlane_b32 s3, v252, 49
	s_nop 0
	s_nop 0
	s_nop 2
	global_load_dword v9, v99, s[2:3] sc1
	v_readlane_b32 s2, v252, 50
	v_readlane_b32 s3, v252, 51
	s_nop 0
	s_nop 0
	s_nop 2
	global_load_dword v10, v99, s[2:3] sc1
	v_readlane_b32 s2, v252, 52
	v_readlane_b32 s3, v252, 53
	s_nop 0
	s_nop 0
	s_nop 2
	global_load_dword v11, v99, s[2:3] sc1
	v_readlane_b32 s2, v252, 54
	v_readlane_b32 s3, v252, 55
	s_nop 0
	s_nop 0
	s_nop 2
	global_load_dword v12, v99, s[2:3] sc1
	v_readlane_b32 s2, v252, 56
	v_readlane_b32 s3, v252, 57
	s_nop 0
	s_nop 0
	s_nop 2
	global_load_dword v13, v99, s[2:3] sc1
	v_readlane_b32 s2, v252, 58
	v_readlane_b32 s3, v252, 59
	s_nop 0
	s_nop 0
	s_nop 2
	global_load_dword v14, v99, s[2:3] sc1
	v_readlane_b32 s2, v252, 60
	v_readlane_b32 s3, v252, 61
	s_nop 0
	s_nop 0
	s_nop 2
	global_load_dword v15, v99, s[2:3] sc1
	v_readlane_b32 s2, v252, 62
	v_readlane_b32 s3, v252, 63
	s_nop 0
	s_nop 0
	s_nop 2
	global_load_dword v16, v99, s[2:3] sc1
	v_readlane_b32 s2, v253, 0
	v_readlane_b32 s3, v253, 1
	s_nop 0
	s_nop 0
	s_nop 2
	global_load_dword v17, v99, s[2:3] sc1
	s_waitcnt vmcnt(0)
	v_cmp_eq_u32_e32 vcc, s1, v2
	v_cmp_eq_u32_e64 s[6:7], s1, v4
	v_cmp_eq_u32_e64 s[8:9], s1, v5
	v_cmp_eq_u32_e64 s[10:11], s1, v6
	v_cmp_eq_u32_e64 s[40:41], s1, v7
	v_cmp_eq_u32_e64 s[42:43], s1, v8
	v_cmp_eq_u32_e64 s[44:45], s1, v9
	v_cmp_eq_u32_e64 s[46:47], 0, v10
	v_cmp_eq_u32_e64 s[48:49], 0, v11
	v_cmp_eq_u32_e64 s[50:51], 0, v12
	v_cmp_eq_u32_e64 s[52:53], 0, v13
	v_cmp_eq_u32_e64 s[54:55], 0, v14
	v_cmp_eq_u32_e64 s[56:57], 0, v15
	v_cmp_eq_u32_e64 s[58:59], 0, v16
	s_and_b64 s[16:17], s[16:17], vcc
	v_cmp_eq_u32_e64 s[2:3], s1, v3
	s_and_b64 s[2:3], s[16:17], s[2:3]
	s_and_b64 s[2:3], s[2:3], s[6:7]
	s_and_b64 s[2:3], s[2:3], s[8:9]
	s_and_b64 s[2:3], s[2:3], s[10:11]
	s_and_b64 s[2:3], s[2:3], s[40:41]
	s_and_b64 s[2:3], s[2:3], s[42:43]
	s_and_b64 s[2:3], s[2:3], s[44:45]
	s_and_b64 s[2:3], s[2:3], s[46:47]
	s_and_b64 s[2:3], s[2:3], s[48:49]
	s_and_b64 s[2:3], s[2:3], s[50:51]
	s_and_b64 s[2:3], s[2:3], s[52:53]
	ds_read_b32 v1, v1
	s_and_b64 s[2:3], s[2:3], s[54:55]
	s_and_b64 s[2:3], s[2:3], s[56:57]
	s_and_b64 s[2:3], s[2:3], s[58:59]
	s_waitcnt vmcnt(0)
	v_cmp_eq_u32_e64 s[60:61], 0, v17
	s_and_b64 s[2:3], s[2:3], s[60:61]
	s_andn2_b64 vcc, exec, s[2:3]
	s_mov_b64 s[2:3], -1
	s_cbranch_vccz .LBB0_481
	v_readlane_b32 s1, v255, 24
	s_mov_b64 s[2:3], 0
	s_nop 0
	v_mov_b32_e32 v2, s1
	ds_write_b32 v2, v226
